# gate/up epilogue: the +1 of the sigmoid back to two scalar adds instead of one packed add with an inline constant (everything else as the 1165.9 us version)
# baseline (speedup 1.0000x reference)
; __device__ __forceinline__ float siluf_(float x) { return x * sigmoidf_(x); }
; __device__ __forceinline__ float rinv_of(float ssq) { return rsqrtf(ssq * (1.0f / 1024.0f) + EPS); }
; __device__ __forceinline__ u32x4 pack8(const f32x4 a, const f32x4 b) { u32x4 w; w.x = cvt_pk_bf16(a[0], a[1]); w.y = cvt_pk_bf16(a[2], a[3]); w.z = cvt_pk_bf16(b[0], b[1]); w.w = cvt_pk_bf16(b[2], b[3]); return w; }
;     __device__ __forceinline__ void operator()(const AccT& acc, const pg8::Unit& u, int wr, int wc, int fr, int fq) const {
;     ...
;         float ris[2][4];
; #pragma unroll
;         for (int ai = 0; ai < 2; ++ai)
; #pragma unroll
;             for (int m = 0; m < 4; ++m) ris[ai][m] = ssq_in[EPI_ROW(u, ai, m)];
; #pragma unroll
;         for (int ai = 0; ai < 2; ++ai)
; #pragma unroll
;             for (int m = 0; m < 4; ++m) {
;                 const int r = EPI_ROW(u, ai, m); const float ri = rinv_of(ris[ai][m]);
;                 f32x4 o[2];
; #pragma unroll
;                 for (int n = 0; n < 2; ++n) { const f32x4 gt = acc[ai][0][m][n] * ri, up = acc[ai][1][m][n] * ri;
; #pragma unroll
;                     for (int j = 0; j < 4; ++j) o[n][j] = siluf_(gt[j]) * up[j]; }
;                 *(u32x4*)(act + (size_t)r * DFF + u.pn * 128 + wc * 32 + 8 * fq) = pack8(o[0], o[1]); }
.LBB0_1535:
	s_lshl_b32 s98, s24, 8
	s_lshl_b32 s99, s35, 6
	s_add_i32 s98, s98, s99
	v_add_u32_e32 v160, s98, v148
	v_lshlrev_b32_e32 v168, 2, v160
	s_waitcnt vmcnt(16)
	s_lshl_b32 s98, s25, 7
	s_lshl_b32 s99, s42, 5
	s_add_i32 s98, s98, s99
	v_lshl_add_u32 v161, v149, 3, s98
	v_lshlrev_b32_e32 v161, 1, v161
	v_mul_u32_u24_e32 v169, 0x1600, v160
	v_add_u32_e32 v161, v161, v169
	s_add_u32 s100, s54, 0x9a2dc00
	s_addc_u32 s101, s55, 0
	v_mov_b32_e32 v188, 0x358637bd
	v_fmamk_f32 v162, v248, 0x3a800000, v188
	v_rsq_f32_e32 v162, v162
	v_mov_b32_e32 v168, v161
	s_nop 0
	v_mul_f32_e32 v170, 0xbfb8aa3b, v162
	v_mul_f32_e32 v162, v162, v162
	v_pk_mul_f32 v[164:165], v[116:117], v[170:171] op_sel_hi:[1,0]
	v_pk_mul_f32 v[166:167], v[118:119], v[170:171] op_sel_hi:[1,0]
	v_exp_f32_e32 v164, v164
	v_exp_f32_e32 v165, v165
	v_exp_f32_e32 v166, v166
	v_exp_f32_e32 v167, v167
	v_pk_mul_f32 v[116:117], v[116:117], v[124:125]
	v_pk_mul_f32 v[118:119], v[118:119], v[126:127]
	v_add_f32_e32 v164, 1.0, v164
	v_add_f32_e32 v165, 1.0, v165
	v_add_f32_e32 v166, 1.0, v166
	v_add_f32_e32 v167, 1.0, v167
	v_rcp_f32_e32 v164, v164
	v_rcp_f32_e32 v165, v165
	v_rcp_f32_e32 v166, v166
	v_rcp_f32_e32 v167, v167
	v_pk_mul_f32 v[116:117], v[116:117], v[162:163] op_sel_hi:[1,0]
	v_pk_mul_f32 v[118:119], v[118:119], v[162:163] op_sel_hi:[1,0]
	v_pk_mul_f32 v[116:117], v[116:117], v[164:165]
	v_pk_mul_f32 v[118:119], v[118:119], v[166:167]
	v_pk_mul_f32 v[164:165], v[112:113], v[170:171] op_sel_hi:[1,0]
	v_pk_mul_f32 v[166:167], v[114:115], v[170:171] op_sel_hi:[1,0]
	v_exp_f32_e32 v164, v164
	v_exp_f32_e32 v165, v165
	v_exp_f32_e32 v166, v166
	v_exp_f32_e32 v167, v167
	v_pk_mul_f32 v[112:113], v[112:113], v[120:121]
	v_pk_mul_f32 v[114:115], v[114:115], v[122:123]
	v_add_f32_e32 v164, 1.0, v164
	v_add_f32_e32 v165, 1.0, v165
	v_add_f32_e32 v166, 1.0, v166
	v_add_f32_e32 v167, 1.0, v167
	v_rcp_f32_e32 v164, v164
	v_rcp_f32_e32 v165, v165
	v_rcp_f32_e32 v166, v166
	v_rcp_f32_e32 v167, v167
	v_pk_mul_f32 v[112:113], v[112:113], v[162:163] op_sel_hi:[1,0]
	v_pk_mul_f32 v[114:115], v[114:115], v[162:163] op_sel_hi:[1,0]
	v_pk_mul_f32 v[112:113], v[112:113], v[164:165]
	v_pk_mul_f32 v[114:115], v[114:115], v[166:167]
	v_cvt_pk_bf16_f32 v172, v116, v117
	v_cvt_pk_bf16_f32 v173, v118, v119
	v_cvt_pk_bf16_f32 v174, v112, v113
	v_cvt_pk_bf16_f32 v175, v114, v115
	global_store_dwordx4 v168, v[172:175], s[100:101]
	v_fmamk_f32 v162, v249, 0x3a800000, v188
	v_rsq_f32_e32 v162, v162
	v_add_u32_e32 v168, 0x16000, v161
	s_nop 0
	v_mul_f32_e32 v170, 0xbfb8aa3b, v162
	v_mul_f32_e32 v162, v162, v162
	v_pk_mul_f32 v[164:165], v[104:105], v[170:171] op_sel_hi:[1,0]
	v_pk_mul_f32 v[166:167], v[106:107], v[170:171] op_sel_hi:[1,0]
	v_exp_f32_e32 v164, v164
	v_exp_f32_e32 v165, v165
	v_exp_f32_e32 v166, v166
	v_exp_f32_e32 v167, v167
	v_pk_mul_f32 v[104:105], v[104:105], v[108:109]
	v_pk_mul_f32 v[106:107], v[106:107], v[110:111]
	v_add_f32_e32 v164, 1.0, v164
	v_add_f32_e32 v165, 1.0, v165
	v_add_f32_e32 v166, 1.0, v166
	v_add_f32_e32 v167, 1.0, v167
	v_rcp_f32_e32 v164, v164
	v_rcp_f32_e32 v165, v165
	v_rcp_f32_e32 v166, v166
	v_rcp_f32_e32 v167, v167
	v_pk_mul_f32 v[104:105], v[104:105], v[162:163] op_sel_hi:[1,0]
	v_pk_mul_f32 v[106:107], v[106:107], v[162:163] op_sel_hi:[1,0]
	v_pk_mul_f32 v[104:105], v[104:105], v[164:165]
	v_pk_mul_f32 v[106:107], v[106:107], v[166:167]
	v_pk_mul_f32 v[164:165], v[96:97], v[170:171] op_sel_hi:[1,0]
	v_pk_mul_f32 v[166:167], v[98:99], v[170:171] op_sel_hi:[1,0]
	v_exp_f32_e32 v164, v164
	v_exp_f32_e32 v165, v165
	v_exp_f32_e32 v166, v166
	v_exp_f32_e32 v167, v167
	v_pk_mul_f32 v[96:97], v[96:97], v[100:101]
	v_pk_mul_f32 v[98:99], v[98:99], v[102:103]
	v_add_f32_e32 v164, 1.0, v164
	v_add_f32_e32 v165, 1.0, v165
	v_add_f32_e32 v166, 1.0, v166
	v_add_f32_e32 v167, 1.0, v167
	v_rcp_f32_e32 v164, v164
	v_rcp_f32_e32 v165, v165
	v_rcp_f32_e32 v166, v166
	v_rcp_f32_e32 v167, v167
	v_pk_mul_f32 v[96:97], v[96:97], v[162:163] op_sel_hi:[1,0]
	v_pk_mul_f32 v[98:99], v[98:99], v[162:163] op_sel_hi:[1,0]
	v_pk_mul_f32 v[96:97], v[96:97], v[164:165]
	v_pk_mul_f32 v[98:99], v[98:99], v[166:167]
	v_cvt_pk_bf16_f32 v176, v104, v105
	v_cvt_pk_bf16_f32 v177, v106, v107
	v_cvt_pk_bf16_f32 v178, v96, v97
	v_cvt_pk_bf16_f32 v179, v98, v99
	global_store_dwordx4 v168, v[176:179], s[100:101]
	v_fmamk_f32 v162, v250, 0x3a800000, v188
	v_rsq_f32_e32 v162, v162
	v_add_u32_e32 v168, 0x2c000, v161
	s_nop 0
	v_mul_f32_e32 v170, 0xbfb8aa3b, v162
	v_mul_f32_e32 v162, v162, v162
	v_pk_mul_f32 v[164:165], v[88:89], v[170:171] op_sel_hi:[1,0]
	v_pk_mul_f32 v[166:167], v[90:91], v[170:171] op_sel_hi:[1,0]
	v_exp_f32_e32 v164, v164
	v_exp_f32_e32 v165, v165
	v_exp_f32_e32 v166, v166
	v_exp_f32_e32 v167, v167
	v_pk_mul_f32 v[88:89], v[88:89], v[92:93]
	v_pk_mul_f32 v[90:91], v[90:91], v[94:95]
	v_add_f32_e32 v164, 1.0, v164
	v_add_f32_e32 v165, 1.0, v165
	v_add_f32_e32 v166, 1.0, v166
	v_add_f32_e32 v167, 1.0, v167
	v_rcp_f32_e32 v164, v164
	v_rcp_f32_e32 v165, v165
	v_rcp_f32_e32 v166, v166
	v_rcp_f32_e32 v167, v167
	v_pk_mul_f32 v[88:89], v[88:89], v[162:163] op_sel_hi:[1,0]
	v_pk_mul_f32 v[90:91], v[90:91], v[162:163] op_sel_hi:[1,0]
	v_pk_mul_f32 v[88:89], v[88:89], v[164:165]
	v_pk_mul_f32 v[90:91], v[90:91], v[166:167]
	v_pk_mul_f32 v[164:165], v[80:81], v[170:171] op_sel_hi:[1,0]
	v_pk_mul_f32 v[166:167], v[82:83], v[170:171] op_sel_hi:[1,0]
	v_exp_f32_e32 v164, v164
	v_exp_f32_e32 v165, v165
	v_exp_f32_e32 v166, v166
	v_exp_f32_e32 v167, v167
	v_pk_mul_f32 v[80:81], v[80:81], v[84:85]
	v_pk_mul_f32 v[82:83], v[82:83], v[86:87]
	v_add_f32_e32 v164, 1.0, v164
	v_add_f32_e32 v165, 1.0, v165
; __device__ __forceinline__ float siluf_(float x) { return x * sigmoidf_(x); }
; __device__ __forceinline__ float rinv_of(float ssq) { return rsqrtf(ssq * (1.0f / 1024.0f) + EPS); }
; __device__ __forceinline__ u32x4 pack8(const f32x4 a, const f32x4 b) { u32x4 w; w.x = cvt_pk_bf16(a[0], a[1]); w.y = cvt_pk_bf16(a[2], a[3]); w.z = cvt_pk_bf16(b[0], b[1]); w.w = cvt_pk_bf16(b[2], b[3]); return w; }
;     __device__ __forceinline__ void operator()(const AccT& acc, const pg8::Unit& u, int wr, int wc, int fr, int fq) const {
;     ...
;                 const int r = EPI_ROW(u, ai, m); const float ri = rinv_of(ris[ai][m]);
;                 f32x4 o[2];
; #pragma unroll
;                 for (int n = 0; n < 2; ++n) { const f32x4 gt = acc[ai][0][m][n] * ri, up = acc[ai][1][m][n] * ri;
; #pragma unroll
;                     for (int j = 0; j < 4; ++j) o[n][j] = siluf_(gt[j]) * up[j]; }
;                 *(u32x4*)(act + (size_t)r * DFF + u.pn * 128 + wc * 32 + 8 * fq) = pack8(o[0], o[1]); }
	v_add_f32_e32 v166, 1.0, v166
	v_add_f32_e32 v167, 1.0, v167
	v_rcp_f32_e32 v164, v164
	v_rcp_f32_e32 v165, v165
	v_rcp_f32_e32 v166, v166
	v_rcp_f32_e32 v167, v167
	v_pk_mul_f32 v[80:81], v[80:81], v[162:163] op_sel_hi:[1,0]
	v_pk_mul_f32 v[82:83], v[82:83], v[162:163] op_sel_hi:[1,0]
	v_pk_mul_f32 v[80:81], v[80:81], v[164:165]
	v_pk_mul_f32 v[82:83], v[82:83], v[166:167]
	v_cvt_pk_bf16_f32 v172, v88, v89
	v_cvt_pk_bf16_f32 v173, v90, v91
	v_cvt_pk_bf16_f32 v174, v80, v81
	v_cvt_pk_bf16_f32 v175, v82, v83
	global_store_dwordx4 v168, v[172:175], s[100:101]
	v_fmamk_f32 v162, v251, 0x3a800000, v188
	v_rsq_f32_e32 v162, v162
	v_add_u32_e32 v168, 0x42000, v161
	s_nop 0
	v_mul_f32_e32 v170, 0xbfb8aa3b, v162
	v_mul_f32_e32 v162, v162, v162
	v_pk_mul_f32 v[164:165], v[72:73], v[170:171] op_sel_hi:[1,0]
	v_pk_mul_f32 v[166:167], v[74:75], v[170:171] op_sel_hi:[1,0]
	v_exp_f32_e32 v164, v164
	v_exp_f32_e32 v165, v165
	v_exp_f32_e32 v166, v166
	v_exp_f32_e32 v167, v167
	v_pk_mul_f32 v[72:73], v[72:73], v[76:77]
	v_pk_mul_f32 v[74:75], v[74:75], v[78:79]
	v_add_f32_e32 v164, 1.0, v164
	v_add_f32_e32 v165, 1.0, v165
	v_add_f32_e32 v166, 1.0, v166
	v_add_f32_e32 v167, 1.0, v167
	v_rcp_f32_e32 v164, v164
	v_rcp_f32_e32 v165, v165
	v_rcp_f32_e32 v166, v166
	v_rcp_f32_e32 v167, v167
	v_pk_mul_f32 v[72:73], v[72:73], v[162:163] op_sel_hi:[1,0]
	v_pk_mul_f32 v[74:75], v[74:75], v[162:163] op_sel_hi:[1,0]
	v_pk_mul_f32 v[72:73], v[72:73], v[164:165]
	v_pk_mul_f32 v[74:75], v[74:75], v[166:167]
	v_pk_mul_f32 v[164:165], v[64:65], v[170:171] op_sel_hi:[1,0]
	v_pk_mul_f32 v[166:167], v[66:67], v[170:171] op_sel_hi:[1,0]
	v_exp_f32_e32 v164, v164
	v_exp_f32_e32 v165, v165
	v_exp_f32_e32 v166, v166
	v_exp_f32_e32 v167, v167
	v_pk_mul_f32 v[64:65], v[64:65], v[68:69]
	v_pk_mul_f32 v[66:67], v[66:67], v[70:71]
	v_add_f32_e32 v164, 1.0, v164
	v_add_f32_e32 v165, 1.0, v165
	v_add_f32_e32 v166, 1.0, v166
	v_add_f32_e32 v167, 1.0, v167
	v_rcp_f32_e32 v164, v164
	v_rcp_f32_e32 v165, v165
	v_rcp_f32_e32 v166, v166
	v_rcp_f32_e32 v167, v167
	v_pk_mul_f32 v[64:65], v[64:65], v[162:163] op_sel_hi:[1,0]
	v_pk_mul_f32 v[66:67], v[66:67], v[162:163] op_sel_hi:[1,0]
	v_pk_mul_f32 v[64:65], v[64:65], v[164:165]
	v_pk_mul_f32 v[66:67], v[66:67], v[166:167]
	v_cvt_pk_bf16_f32 v176, v72, v73
	v_cvt_pk_bf16_f32 v177, v74, v75
	v_cvt_pk_bf16_f32 v178, v64, v65
	v_cvt_pk_bf16_f32 v179, v66, v67
	global_store_dwordx4 v168, v[176:179], s[100:101]
	v_fmamk_f32 v162, v252, 0x3a800000, v188
	v_rsq_f32_e32 v162, v162
	v_add_u32_e32 v168, 0xb0000, v161
	s_nop 0
	v_mul_f32_e32 v170, 0xbfb8aa3b, v162
	v_mul_f32_e32 v162, v162, v162
	v_pk_mul_f32 v[164:165], v[56:57], v[170:171] op_sel_hi:[1,0]
	v_pk_mul_f32 v[166:167], v[58:59], v[170:171] op_sel_hi:[1,0]
	v_exp_f32_e32 v164, v164
	v_exp_f32_e32 v165, v165
	v_exp_f32_e32 v166, v166
	v_exp_f32_e32 v167, v167
	v_pk_mul_f32 v[56:57], v[56:57], v[60:61]
	v_pk_mul_f32 v[58:59], v[58:59], v[62:63]
	v_add_f32_e32 v164, 1.0, v164
	v_add_f32_e32 v165, 1.0, v165
	v_add_f32_e32 v166, 1.0, v166
	v_add_f32_e32 v167, 1.0, v167
	v_rcp_f32_e32 v164, v164
	v_rcp_f32_e32 v165, v165
	v_rcp_f32_e32 v166, v166
	v_rcp_f32_e32 v167, v167
	v_pk_mul_f32 v[56:57], v[56:57], v[162:163] op_sel_hi:[1,0]
	v_pk_mul_f32 v[58:59], v[58:59], v[162:163] op_sel_hi:[1,0]
	v_pk_mul_f32 v[56:57], v[56:57], v[164:165]
	v_pk_mul_f32 v[58:59], v[58:59], v[166:167]
	v_pk_mul_f32 v[164:165], v[48:49], v[170:171] op_sel_hi:[1,0]
	v_pk_mul_f32 v[166:167], v[50:51], v[170:171] op_sel_hi:[1,0]
	v_exp_f32_e32 v164, v164
	v_exp_f32_e32 v165, v165
	v_exp_f32_e32 v166, v166
	v_exp_f32_e32 v167, v167
	v_pk_mul_f32 v[48:49], v[48:49], v[52:53]
	v_pk_mul_f32 v[50:51], v[50:51], v[54:55]
	v_add_f32_e32 v164, 1.0, v164
	v_add_f32_e32 v165, 1.0, v165
	v_add_f32_e32 v166, 1.0, v166
	v_add_f32_e32 v167, 1.0, v167
	v_rcp_f32_e32 v164, v164
	v_rcp_f32_e32 v165, v165
	v_rcp_f32_e32 v166, v166
	v_rcp_f32_e32 v167, v167
	v_pk_mul_f32 v[48:49], v[48:49], v[162:163] op_sel_hi:[1,0]
	v_pk_mul_f32 v[50:51], v[50:51], v[162:163] op_sel_hi:[1,0]
	v_pk_mul_f32 v[48:49], v[48:49], v[164:165]
	v_pk_mul_f32 v[50:51], v[50:51], v[166:167]
	v_cvt_pk_bf16_f32 v172, v56, v57
	v_cvt_pk_bf16_f32 v173, v58, v59
	v_cvt_pk_bf16_f32 v174, v48, v49
	v_cvt_pk_bf16_f32 v175, v50, v51
	global_store_dwordx4 v168, v[172:175], s[100:101]
	v_fmamk_f32 v162, v253, 0x3a800000, v188
	v_rsq_f32_e32 v162, v162
	v_add_u32_e32 v168, 0xc6000, v161
	s_nop 0
	v_mul_f32_e32 v170, 0xbfb8aa3b, v162
	v_mul_f32_e32 v162, v162, v162
	v_pk_mul_f32 v[164:165], v[40:41], v[170:171] op_sel_hi:[1,0]
	v_pk_mul_f32 v[166:167], v[42:43], v[170:171] op_sel_hi:[1,0]
	v_exp_f32_e32 v164, v164
	v_exp_f32_e32 v165, v165
	v_exp_f32_e32 v166, v166
	v_exp_f32_e32 v167, v167
	v_pk_mul_f32 v[40:41], v[40:41], v[44:45]
	v_pk_mul_f32 v[42:43], v[42:43], v[46:47]
	v_add_f32_e32 v164, 1.0, v164
	v_add_f32_e32 v165, 1.0, v165
	v_add_f32_e32 v166, 1.0, v166
	v_add_f32_e32 v167, 1.0, v167
	v_rcp_f32_e32 v164, v164
	v_rcp_f32_e32 v165, v165
	v_rcp_f32_e32 v166, v166
; __device__ __forceinline__ float siluf_(float x) { return x * sigmoidf_(x); }
; __device__ __forceinline__ float rinv_of(float ssq) { return rsqrtf(ssq * (1.0f / 1024.0f) + EPS); }
; __device__ __forceinline__ u32x4 pack8(const f32x4 a, const f32x4 b) { u32x4 w; w.x = cvt_pk_bf16(a[0], a[1]); w.y = cvt_pk_bf16(a[2], a[3]); w.z = cvt_pk_bf16(b[0], b[1]); w.w = cvt_pk_bf16(b[2], b[3]); return w; }
;     __device__ __forceinline__ void operator()(const AccT& acc, const pg8::Unit& u, int wr, int wc, int fr, int fq) const {
;     ...
;                 const int r = EPI_ROW(u, ai, m); const float ri = rinv_of(ris[ai][m]);
;                 f32x4 o[2];
; #pragma unroll
;                 for (int n = 0; n < 2; ++n) { const f32x4 gt = acc[ai][0][m][n] * ri, up = acc[ai][1][m][n] * ri;
; #pragma unroll
;                     for (int j = 0; j < 4; ++j) o[n][j] = siluf_(gt[j]) * up[j]; }
;                 *(u32x4*)(act + (size_t)r * DFF + u.pn * 128 + wc * 32 + 8 * fq) = pack8(o[0], o[1]); }
	v_rcp_f32_e32 v167, v167
	v_pk_mul_f32 v[40:41], v[40:41], v[162:163] op_sel_hi:[1,0]
	v_pk_mul_f32 v[42:43], v[42:43], v[162:163] op_sel_hi:[1,0]
	v_pk_mul_f32 v[40:41], v[40:41], v[164:165]
	v_pk_mul_f32 v[42:43], v[42:43], v[166:167]
	v_pk_mul_f32 v[164:165], v[32:33], v[170:171] op_sel_hi:[1,0]
	v_pk_mul_f32 v[166:167], v[34:35], v[170:171] op_sel_hi:[1,0]
	v_exp_f32_e32 v164, v164
	v_exp_f32_e32 v165, v165
	v_exp_f32_e32 v166, v166
	v_exp_f32_e32 v167, v167
	v_pk_mul_f32 v[32:33], v[32:33], v[36:37]
	v_pk_mul_f32 v[34:35], v[34:35], v[38:39]
	v_add_f32_e32 v164, 1.0, v164
	v_add_f32_e32 v165, 1.0, v165
	v_add_f32_e32 v166, 1.0, v166
	v_add_f32_e32 v167, 1.0, v167
	v_rcp_f32_e32 v164, v164
	v_rcp_f32_e32 v165, v165
	v_rcp_f32_e32 v166, v166
	v_rcp_f32_e32 v167, v167
	v_pk_mul_f32 v[32:33], v[32:33], v[162:163] op_sel_hi:[1,0]
	v_pk_mul_f32 v[34:35], v[34:35], v[162:163] op_sel_hi:[1,0]
	v_pk_mul_f32 v[32:33], v[32:33], v[164:165]
	v_pk_mul_f32 v[34:35], v[34:35], v[166:167]
	v_cvt_pk_bf16_f32 v176, v40, v41
	v_cvt_pk_bf16_f32 v177, v42, v43
	v_cvt_pk_bf16_f32 v178, v32, v33
	v_cvt_pk_bf16_f32 v179, v34, v35
	global_store_dwordx4 v168, v[176:179], s[100:101]
	v_fmamk_f32 v162, v254, 0x3a800000, v188
	v_rsq_f32_e32 v162, v162
	v_add_u32_e32 v168, 0xdc000, v161
	s_nop 0
	v_mul_f32_e32 v170, 0xbfb8aa3b, v162
	v_mul_f32_e32 v162, v162, v162
	v_pk_mul_f32 v[164:165], v[24:25], v[170:171] op_sel_hi:[1,0]
	v_pk_mul_f32 v[166:167], v[26:27], v[170:171] op_sel_hi:[1,0]
	v_exp_f32_e32 v164, v164
	v_exp_f32_e32 v165, v165
	v_exp_f32_e32 v166, v166
	v_exp_f32_e32 v167, v167
	v_pk_mul_f32 v[24:25], v[24:25], v[28:29]
	v_pk_mul_f32 v[26:27], v[26:27], v[30:31]
	v_add_f32_e32 v164, 1.0, v164
	v_add_f32_e32 v165, 1.0, v165
	v_add_f32_e32 v166, 1.0, v166
	v_add_f32_e32 v167, 1.0, v167
	v_rcp_f32_e32 v164, v164
	v_rcp_f32_e32 v165, v165
	v_rcp_f32_e32 v166, v166
	v_rcp_f32_e32 v167, v167
	v_pk_mul_f32 v[24:25], v[24:25], v[162:163] op_sel_hi:[1,0]
	v_pk_mul_f32 v[26:27], v[26:27], v[162:163] op_sel_hi:[1,0]
	v_pk_mul_f32 v[24:25], v[24:25], v[164:165]
	v_pk_mul_f32 v[26:27], v[26:27], v[166:167]
	v_pk_mul_f32 v[164:165], v[16:17], v[170:171] op_sel_hi:[1,0]
	v_pk_mul_f32 v[166:167], v[18:19], v[170:171] op_sel_hi:[1,0]
	v_exp_f32_e32 v164, v164
	v_exp_f32_e32 v165, v165
	v_exp_f32_e32 v166, v166
	v_exp_f32_e32 v167, v167
	v_pk_mul_f32 v[16:17], v[16:17], v[20:21]
	v_pk_mul_f32 v[18:19], v[18:19], v[22:23]
	v_add_f32_e32 v164, 1.0, v164
	v_add_f32_e32 v165, 1.0, v165
	v_add_f32_e32 v166, 1.0, v166
	v_add_f32_e32 v167, 1.0, v167
	v_rcp_f32_e32 v164, v164
	v_rcp_f32_e32 v165, v165
	v_rcp_f32_e32 v166, v166
	v_rcp_f32_e32 v167, v167
	v_pk_mul_f32 v[16:17], v[16:17], v[162:163] op_sel_hi:[1,0]
	v_pk_mul_f32 v[18:19], v[18:19], v[162:163] op_sel_hi:[1,0]
	v_pk_mul_f32 v[16:17], v[16:17], v[164:165]
	v_pk_mul_f32 v[18:19], v[18:19], v[166:167]
	v_cvt_pk_bf16_f32 v172, v24, v25
	v_cvt_pk_bf16_f32 v173, v26, v27
	v_cvt_pk_bf16_f32 v174, v16, v17
	v_cvt_pk_bf16_f32 v175, v18, v19
	global_store_dwordx4 v168, v[172:175], s[100:101]
	v_fmamk_f32 v162, v255, 0x3a800000, v188
	v_rsq_f32_e32 v162, v162
	v_add_u32_e32 v168, 0xf2000, v161
	s_nop 0
	v_mul_f32_e32 v170, 0xbfb8aa3b, v162
	v_mul_f32_e32 v162, v162, v162
	v_pk_mul_f32 v[164:165], v[8:9], v[170:171] op_sel_hi:[1,0]
	v_pk_mul_f32 v[166:167], v[10:11], v[170:171] op_sel_hi:[1,0]
	v_exp_f32_e32 v164, v164
	v_exp_f32_e32 v165, v165
	v_exp_f32_e32 v166, v166
	v_exp_f32_e32 v167, v167
	v_pk_mul_f32 v[8:9], v[8:9], v[12:13]
	v_pk_mul_f32 v[10:11], v[10:11], v[14:15]
	v_add_f32_e32 v164, 1.0, v164
	v_add_f32_e32 v165, 1.0, v165
	v_add_f32_e32 v166, 1.0, v166
	v_add_f32_e32 v167, 1.0, v167
	v_rcp_f32_e32 v164, v164
	v_rcp_f32_e32 v165, v165
	v_rcp_f32_e32 v166, v166
	v_rcp_f32_e32 v167, v167
	v_pk_mul_f32 v[8:9], v[8:9], v[162:163] op_sel_hi:[1,0]
	v_pk_mul_f32 v[10:11], v[10:11], v[162:163] op_sel_hi:[1,0]
	v_pk_mul_f32 v[8:9], v[8:9], v[164:165]
	v_pk_mul_f32 v[10:11], v[10:11], v[166:167]
	v_pk_mul_f32 v[164:165], v[4:5], v[170:171] op_sel_hi:[1,0]
	v_pk_mul_f32 v[166:167], v[6:7], v[170:171] op_sel_hi:[1,0]
	v_exp_f32_e32 v164, v164
	v_exp_f32_e32 v165, v165
	v_exp_f32_e32 v166, v166
	v_exp_f32_e32 v167, v167
	v_pk_mul_f32 v[4:5], v[4:5], v[0:1]
	v_pk_mul_f32 v[6:7], v[6:7], v[2:3]
	v_add_f32_e32 v164, 1.0, v164
	v_add_f32_e32 v165, 1.0, v165
	v_add_f32_e32 v166, 1.0, v166
	v_add_f32_e32 v167, 1.0, v167
	v_rcp_f32_e32 v164, v164
	v_rcp_f32_e32 v165, v165
	v_rcp_f32_e32 v166, v166
	v_rcp_f32_e32 v167, v167
	v_pk_mul_f32 v[4:5], v[4:5], v[162:163] op_sel_hi:[1,0]
	v_pk_mul_f32 v[6:7], v[6:7], v[162:163] op_sel_hi:[1,0]
	v_pk_mul_f32 v[4:5], v[4:5], v[164:165]
	v_pk_mul_f32 v[6:7], v[6:7], v[166:167]
	v_cvt_pk_bf16_f32 v176, v8, v9
	v_cvt_pk_bf16_f32 v177, v10, v11
	v_cvt_pk_bf16_f32 v178, v4, v5
	v_cvt_pk_bf16_f32 v179, v6, v7
	global_store_dwordx4 v168, v[176:179], s[100:101]
	s_mov_b64 s[28:29], s[18:19]
	s_mov_b32 s25, s14
	s_mov_b32 s24, s16
	s_mov_b64 s[26:27], s[22:23]
	s_and_b64 vcc, exec, s[6:7]
	s_cbranch_vccnz .LBB0_1545

; __device__ __forceinline__ float siluf_(float x) { return x * sigmoidf_(x); }
; __device__ __forceinline__ float rinv_of(float ssq) { return rsqrtf(ssq * (1.0f / 1024.0f) + EPS); }
; __device__ __forceinline__ u32x4 pack8(const f32x4 a, const f32x4 b) { u32x4 w; w.x = cvt_pk_bf16(a[0], a[1]); w.y = cvt_pk_bf16(a[2], a[3]); w.z = cvt_pk_bf16(b[0], b[1]); w.w = cvt_pk_bf16(b[2], b[3]); return w; }
;     __device__ __forceinline__ void operator()(const AccT& acc, const pg8::Unit& u, int wr, int wc, int fr, int fq) const {
;     ...
;         float ris[2][4];
; #pragma unroll
;         for (int ai = 0; ai < 2; ++ai)
; #pragma unroll
;             for (int m = 0; m < 4; ++m) ris[ai][m] = ssq_in[EPI_ROW(u, ai, m)];
; #pragma unroll
;         for (int ai = 0; ai < 2; ++ai)
; #pragma unroll
;             for (int m = 0; m < 4; ++m) {
;                 const int r = EPI_ROW(u, ai, m); const float ri = rinv_of(ris[ai][m]);
;                 f32x4 o[2];
; #pragma unroll
;                 for (int n = 0; n < 2; ++n) { const f32x4 gt = acc[ai][0][m][n] * ri, up = acc[ai][1][m][n] * ri;
; #pragma unroll
;                     for (int j = 0; j < 4; ++j) o[n][j] = siluf_(gt[j]) * up[j]; }
;                 *(u32x4*)(act + (size_t)r * DFF + u.pn * 128 + wc * 32 + 8 * fq) = pack8(o[0], o[1]); }
.LBB0_2402:
	s_lshl_b32 s98, s24, 8
	s_lshl_b32 s99, s35, 6
	s_add_i32 s98, s98, s99
	v_add_u32_e32 v160, s98, v148
	v_lshlrev_b32_e32 v168, 2, v160
	s_waitcnt vmcnt(16)
	s_lshl_b32 s98, s25, 7
	s_lshl_b32 s99, s42, 5
	s_add_i32 s98, s98, s99
	v_lshl_add_u32 v161, v149, 3, s98
	v_lshlrev_b32_e32 v161, 1, v161
	v_mul_u32_u24_e32 v169, 0x1600, v160
	v_add_u32_e32 v161, v161, v169
	s_add_u32 s100, s54, 0x9a2dc00
	s_addc_u32 s101, s55, 0
	v_mov_b32_e32 v188, 0x358637bd
	v_fmamk_f32 v162, v248, 0x3a800000, v188
	v_rsq_f32_e32 v162, v162
	v_mov_b32_e32 v168, v161
	s_nop 0
	v_mul_f32_e32 v170, 0xbfb8aa3b, v162
	v_mul_f32_e32 v162, v162, v162
	v_pk_mul_f32 v[164:165], v[116:117], v[170:171] op_sel_hi:[1,0]
	v_pk_mul_f32 v[166:167], v[118:119], v[170:171] op_sel_hi:[1,0]
	v_exp_f32_e32 v164, v164
	v_exp_f32_e32 v165, v165
	v_exp_f32_e32 v166, v166
	v_exp_f32_e32 v167, v167
	v_pk_mul_f32 v[116:117], v[116:117], v[124:125]
	v_pk_mul_f32 v[118:119], v[118:119], v[126:127]
	v_add_f32_e32 v164, 1.0, v164
	v_add_f32_e32 v165, 1.0, v165
	v_add_f32_e32 v166, 1.0, v166
	v_add_f32_e32 v167, 1.0, v167
	v_rcp_f32_e32 v164, v164
	v_rcp_f32_e32 v165, v165
	v_rcp_f32_e32 v166, v166
	v_rcp_f32_e32 v167, v167
	v_pk_mul_f32 v[116:117], v[116:117], v[162:163] op_sel_hi:[1,0]
	v_pk_mul_f32 v[118:119], v[118:119], v[162:163] op_sel_hi:[1,0]
	v_pk_mul_f32 v[116:117], v[116:117], v[164:165]
	v_pk_mul_f32 v[118:119], v[118:119], v[166:167]
	v_pk_mul_f32 v[164:165], v[112:113], v[170:171] op_sel_hi:[1,0]
	v_pk_mul_f32 v[166:167], v[114:115], v[170:171] op_sel_hi:[1,0]
	v_exp_f32_e32 v164, v164
	v_exp_f32_e32 v165, v165
	v_exp_f32_e32 v166, v166
	v_exp_f32_e32 v167, v167
	v_pk_mul_f32 v[112:113], v[112:113], v[120:121]
	v_pk_mul_f32 v[114:115], v[114:115], v[122:123]
	v_add_f32_e32 v164, 1.0, v164
	v_add_f32_e32 v165, 1.0, v165
	v_add_f32_e32 v166, 1.0, v166
	v_add_f32_e32 v167, 1.0, v167
	v_rcp_f32_e32 v164, v164
	v_rcp_f32_e32 v165, v165
	v_rcp_f32_e32 v166, v166
	v_rcp_f32_e32 v167, v167
	v_pk_mul_f32 v[112:113], v[112:113], v[162:163] op_sel_hi:[1,0]
	v_pk_mul_f32 v[114:115], v[114:115], v[162:163] op_sel_hi:[1,0]
	v_pk_mul_f32 v[112:113], v[112:113], v[164:165]
	v_pk_mul_f32 v[114:115], v[114:115], v[166:167]
	v_cvt_pk_bf16_f32 v172, v116, v117
	v_cvt_pk_bf16_f32 v173, v118, v119
	v_cvt_pk_bf16_f32 v174, v112, v113
	v_cvt_pk_bf16_f32 v175, v114, v115
	global_store_dwordx4 v168, v[172:175], s[100:101]
	v_fmamk_f32 v162, v249, 0x3a800000, v188
	v_rsq_f32_e32 v162, v162
	v_add_u32_e32 v168, 0x16000, v161
	s_nop 0
	v_mul_f32_e32 v170, 0xbfb8aa3b, v162
	v_mul_f32_e32 v162, v162, v162
	v_pk_mul_f32 v[164:165], v[104:105], v[170:171] op_sel_hi:[1,0]
	v_pk_mul_f32 v[166:167], v[106:107], v[170:171] op_sel_hi:[1,0]
	v_exp_f32_e32 v164, v164
	v_exp_f32_e32 v165, v165
	v_exp_f32_e32 v166, v166
	v_exp_f32_e32 v167, v167
	v_pk_mul_f32 v[104:105], v[104:105], v[108:109]
	v_pk_mul_f32 v[106:107], v[106:107], v[110:111]
	v_add_f32_e32 v164, 1.0, v164
	v_add_f32_e32 v165, 1.0, v165
	v_add_f32_e32 v166, 1.0, v166
	v_add_f32_e32 v167, 1.0, v167
	v_rcp_f32_e32 v164, v164
	v_rcp_f32_e32 v165, v165
	v_rcp_f32_e32 v166, v166
	v_rcp_f32_e32 v167, v167
	v_pk_mul_f32 v[104:105], v[104:105], v[162:163] op_sel_hi:[1,0]
	v_pk_mul_f32 v[106:107], v[106:107], v[162:163] op_sel_hi:[1,0]
	v_pk_mul_f32 v[104:105], v[104:105], v[164:165]
	v_pk_mul_f32 v[106:107], v[106:107], v[166:167]
	v_pk_mul_f32 v[164:165], v[96:97], v[170:171] op_sel_hi:[1,0]
	v_pk_mul_f32 v[166:167], v[98:99], v[170:171] op_sel_hi:[1,0]
	v_exp_f32_e32 v164, v164
	v_exp_f32_e32 v165, v165
	v_exp_f32_e32 v166, v166
	v_exp_f32_e32 v167, v167
	v_pk_mul_f32 v[96:97], v[96:97], v[100:101]
	v_pk_mul_f32 v[98:99], v[98:99], v[102:103]
	v_add_f32_e32 v164, 1.0, v164
	v_add_f32_e32 v165, 1.0, v165
	v_add_f32_e32 v166, 1.0, v166
	v_add_f32_e32 v167, 1.0, v167
	v_rcp_f32_e32 v164, v164
	v_rcp_f32_e32 v165, v165
	v_rcp_f32_e32 v166, v166
	v_rcp_f32_e32 v167, v167
	v_pk_mul_f32 v[96:97], v[96:97], v[162:163] op_sel_hi:[1,0]
	v_pk_mul_f32 v[98:99], v[98:99], v[162:163] op_sel_hi:[1,0]
	v_pk_mul_f32 v[96:97], v[96:97], v[164:165]
	v_pk_mul_f32 v[98:99], v[98:99], v[166:167]
	v_cvt_pk_bf16_f32 v176, v104, v105
	v_cvt_pk_bf16_f32 v177, v106, v107
	v_cvt_pk_bf16_f32 v178, v96, v97
	v_cvt_pk_bf16_f32 v179, v98, v99
	global_store_dwordx4 v168, v[176:179], s[100:101]
	v_fmamk_f32 v162, v250, 0x3a800000, v188
	v_rsq_f32_e32 v162, v162
	v_add_u32_e32 v168, 0x2c000, v161
	s_nop 0
	v_mul_f32_e32 v170, 0xbfb8aa3b, v162
	v_mul_f32_e32 v162, v162, v162
	v_pk_mul_f32 v[164:165], v[88:89], v[170:171] op_sel_hi:[1,0]
	v_pk_mul_f32 v[166:167], v[90:91], v[170:171] op_sel_hi:[1,0]
	v_exp_f32_e32 v164, v164
	v_exp_f32_e32 v165, v165
	v_exp_f32_e32 v166, v166
	v_exp_f32_e32 v167, v167
	v_pk_mul_f32 v[88:89], v[88:89], v[92:93]
	v_pk_mul_f32 v[90:91], v[90:91], v[94:95]
	v_add_f32_e32 v164, 1.0, v164
	v_add_f32_e32 v165, 1.0, v165
	v_add_f32_e32 v166, 1.0, v166
	v_add_f32_e32 v167, 1.0, v167
	v_rcp_f32_e32 v164, v164
	v_rcp_f32_e32 v165, v165
	v_rcp_f32_e32 v166, v166
	v_rcp_f32_e32 v167, v167
	v_pk_mul_f32 v[88:89], v[88:89], v[162:163] op_sel_hi:[1,0]
	v_pk_mul_f32 v[90:91], v[90:91], v[162:163] op_sel_hi:[1,0]
	v_pk_mul_f32 v[88:89], v[88:89], v[164:165]
	v_pk_mul_f32 v[90:91], v[90:91], v[166:167]
	v_pk_mul_f32 v[164:165], v[80:81], v[170:171] op_sel_hi:[1,0]
	v_pk_mul_f32 v[166:167], v[82:83], v[170:171] op_sel_hi:[1,0]
	v_exp_f32_e32 v164, v164
	v_exp_f32_e32 v165, v165
	v_exp_f32_e32 v166, v166
	v_exp_f32_e32 v167, v167
	v_pk_mul_f32 v[80:81], v[80:81], v[84:85]
	v_pk_mul_f32 v[82:83], v[82:83], v[86:87]
	v_add_f32_e32 v164, 1.0, v164
	v_add_f32_e32 v165, 1.0, v165
; __device__ __forceinline__ float siluf_(float x) { return x * sigmoidf_(x); }
; __device__ __forceinline__ float rinv_of(float ssq) { return rsqrtf(ssq * (1.0f / 1024.0f) + EPS); }
; __device__ __forceinline__ u32x4 pack8(const f32x4 a, const f32x4 b) { u32x4 w; w.x = cvt_pk_bf16(a[0], a[1]); w.y = cvt_pk_bf16(a[2], a[3]); w.z = cvt_pk_bf16(b[0], b[1]); w.w = cvt_pk_bf16(b[2], b[3]); return w; }
;     __device__ __forceinline__ void operator()(const AccT& acc, const pg8::Unit& u, int wr, int wc, int fr, int fq) const {
;     ...
;                 const int r = EPI_ROW(u, ai, m); const float ri = rinv_of(ris[ai][m]);
;                 f32x4 o[2];
; #pragma unroll
;                 for (int n = 0; n < 2; ++n) { const f32x4 gt = acc[ai][0][m][n] * ri, up = acc[ai][1][m][n] * ri;
; #pragma unroll
;                     for (int j = 0; j < 4; ++j) o[n][j] = siluf_(gt[j]) * up[j]; }
;                 *(u32x4*)(act + (size_t)r * DFF + u.pn * 128 + wc * 32 + 8 * fq) = pack8(o[0], o[1]); }
	v_add_f32_e32 v166, 1.0, v166
	v_add_f32_e32 v167, 1.0, v167
	v_rcp_f32_e32 v164, v164
	v_rcp_f32_e32 v165, v165
	v_rcp_f32_e32 v166, v166
	v_rcp_f32_e32 v167, v167
	v_pk_mul_f32 v[80:81], v[80:81], v[162:163] op_sel_hi:[1,0]
	v_pk_mul_f32 v[82:83], v[82:83], v[162:163] op_sel_hi:[1,0]
	v_pk_mul_f32 v[80:81], v[80:81], v[164:165]
	v_pk_mul_f32 v[82:83], v[82:83], v[166:167]
	v_cvt_pk_bf16_f32 v172, v88, v89
	v_cvt_pk_bf16_f32 v173, v90, v91
	v_cvt_pk_bf16_f32 v174, v80, v81
	v_cvt_pk_bf16_f32 v175, v82, v83
	global_store_dwordx4 v168, v[172:175], s[100:101]
	v_fmamk_f32 v162, v251, 0x3a800000, v188
	v_rsq_f32_e32 v162, v162
	v_add_u32_e32 v168, 0x42000, v161
	s_nop 0
	v_mul_f32_e32 v170, 0xbfb8aa3b, v162
	v_mul_f32_e32 v162, v162, v162
	v_pk_mul_f32 v[164:165], v[72:73], v[170:171] op_sel_hi:[1,0]
	v_pk_mul_f32 v[166:167], v[74:75], v[170:171] op_sel_hi:[1,0]
	v_exp_f32_e32 v164, v164
	v_exp_f32_e32 v165, v165
	v_exp_f32_e32 v166, v166
	v_exp_f32_e32 v167, v167
	v_pk_mul_f32 v[72:73], v[72:73], v[76:77]
	v_pk_mul_f32 v[74:75], v[74:75], v[78:79]
	v_add_f32_e32 v164, 1.0, v164
	v_add_f32_e32 v165, 1.0, v165
	v_add_f32_e32 v166, 1.0, v166
	v_add_f32_e32 v167, 1.0, v167
	v_rcp_f32_e32 v164, v164
	v_rcp_f32_e32 v165, v165
	v_rcp_f32_e32 v166, v166
	v_rcp_f32_e32 v167, v167
	v_pk_mul_f32 v[72:73], v[72:73], v[162:163] op_sel_hi:[1,0]
	v_pk_mul_f32 v[74:75], v[74:75], v[162:163] op_sel_hi:[1,0]
	v_pk_mul_f32 v[72:73], v[72:73], v[164:165]
	v_pk_mul_f32 v[74:75], v[74:75], v[166:167]
	v_pk_mul_f32 v[164:165], v[64:65], v[170:171] op_sel_hi:[1,0]
	v_pk_mul_f32 v[166:167], v[66:67], v[170:171] op_sel_hi:[1,0]
	v_exp_f32_e32 v164, v164
	v_exp_f32_e32 v165, v165
	v_exp_f32_e32 v166, v166
	v_exp_f32_e32 v167, v167
	v_pk_mul_f32 v[64:65], v[64:65], v[68:69]
	v_pk_mul_f32 v[66:67], v[66:67], v[70:71]
	v_add_f32_e32 v164, 1.0, v164
	v_add_f32_e32 v165, 1.0, v165
	v_add_f32_e32 v166, 1.0, v166
	v_add_f32_e32 v167, 1.0, v167
	v_rcp_f32_e32 v164, v164
	v_rcp_f32_e32 v165, v165
	v_rcp_f32_e32 v166, v166
	v_rcp_f32_e32 v167, v167
	v_pk_mul_f32 v[64:65], v[64:65], v[162:163] op_sel_hi:[1,0]
	v_pk_mul_f32 v[66:67], v[66:67], v[162:163] op_sel_hi:[1,0]
	v_pk_mul_f32 v[64:65], v[64:65], v[164:165]
	v_pk_mul_f32 v[66:67], v[66:67], v[166:167]
	v_cvt_pk_bf16_f32 v176, v72, v73
	v_cvt_pk_bf16_f32 v177, v74, v75
	v_cvt_pk_bf16_f32 v178, v64, v65
	v_cvt_pk_bf16_f32 v179, v66, v67
	global_store_dwordx4 v168, v[176:179], s[100:101]
	v_fmamk_f32 v162, v252, 0x3a800000, v188
	v_rsq_f32_e32 v162, v162
	v_add_u32_e32 v168, 0xb0000, v161
	s_nop 0
	v_mul_f32_e32 v170, 0xbfb8aa3b, v162
	v_mul_f32_e32 v162, v162, v162
	v_pk_mul_f32 v[164:165], v[56:57], v[170:171] op_sel_hi:[1,0]
	v_pk_mul_f32 v[166:167], v[58:59], v[170:171] op_sel_hi:[1,0]
	v_exp_f32_e32 v164, v164
	v_exp_f32_e32 v165, v165
	v_exp_f32_e32 v166, v166
	v_exp_f32_e32 v167, v167
	v_pk_mul_f32 v[56:57], v[56:57], v[60:61]
	v_pk_mul_f32 v[58:59], v[58:59], v[62:63]
	v_add_f32_e32 v164, 1.0, v164
	v_add_f32_e32 v165, 1.0, v165
	v_add_f32_e32 v166, 1.0, v166
	v_add_f32_e32 v167, 1.0, v167
	v_rcp_f32_e32 v164, v164
	v_rcp_f32_e32 v165, v165
	v_rcp_f32_e32 v166, v166
	v_rcp_f32_e32 v167, v167
	v_pk_mul_f32 v[56:57], v[56:57], v[162:163] op_sel_hi:[1,0]
	v_pk_mul_f32 v[58:59], v[58:59], v[162:163] op_sel_hi:[1,0]
	v_pk_mul_f32 v[56:57], v[56:57], v[164:165]
	v_pk_mul_f32 v[58:59], v[58:59], v[166:167]
	v_pk_mul_f32 v[164:165], v[48:49], v[170:171] op_sel_hi:[1,0]
	v_pk_mul_f32 v[166:167], v[50:51], v[170:171] op_sel_hi:[1,0]
	v_exp_f32_e32 v164, v164
	v_exp_f32_e32 v165, v165
	v_exp_f32_e32 v166, v166
	v_exp_f32_e32 v167, v167
	v_pk_mul_f32 v[48:49], v[48:49], v[52:53]
	v_pk_mul_f32 v[50:51], v[50:51], v[54:55]
	v_add_f32_e32 v164, 1.0, v164
	v_add_f32_e32 v165, 1.0, v165
	v_add_f32_e32 v166, 1.0, v166
	v_add_f32_e32 v167, 1.0, v167
	v_rcp_f32_e32 v164, v164
	v_rcp_f32_e32 v165, v165
	v_rcp_f32_e32 v166, v166
	v_rcp_f32_e32 v167, v167
	v_pk_mul_f32 v[48:49], v[48:49], v[162:163] op_sel_hi:[1,0]
	v_pk_mul_f32 v[50:51], v[50:51], v[162:163] op_sel_hi:[1,0]
	v_pk_mul_f32 v[48:49], v[48:49], v[164:165]
	v_pk_mul_f32 v[50:51], v[50:51], v[166:167]
	v_cvt_pk_bf16_f32 v172, v56, v57
	v_cvt_pk_bf16_f32 v173, v58, v59
	v_cvt_pk_bf16_f32 v174, v48, v49
	v_cvt_pk_bf16_f32 v175, v50, v51
	global_store_dwordx4 v168, v[172:175], s[100:101]
	v_fmamk_f32 v162, v253, 0x3a800000, v188
	v_rsq_f32_e32 v162, v162
	v_add_u32_e32 v168, 0xc6000, v161
	s_nop 0
	v_mul_f32_e32 v170, 0xbfb8aa3b, v162
	v_mul_f32_e32 v162, v162, v162
	v_pk_mul_f32 v[164:165], v[40:41], v[170:171] op_sel_hi:[1,0]
	v_pk_mul_f32 v[166:167], v[42:43], v[170:171] op_sel_hi:[1,0]
	v_exp_f32_e32 v164, v164
	v_exp_f32_e32 v165, v165
	v_exp_f32_e32 v166, v166
	v_exp_f32_e32 v167, v167
	v_pk_mul_f32 v[40:41], v[40:41], v[44:45]
	v_pk_mul_f32 v[42:43], v[42:43], v[46:47]
	v_add_f32_e32 v164, 1.0, v164
	v_add_f32_e32 v165, 1.0, v165
	v_add_f32_e32 v166, 1.0, v166
	v_add_f32_e32 v167, 1.0, v167
	v_rcp_f32_e32 v164, v164
	v_rcp_f32_e32 v165, v165
	v_rcp_f32_e32 v166, v166
; __device__ __forceinline__ float siluf_(float x) { return x * sigmoidf_(x); }
; __device__ __forceinline__ float rinv_of(float ssq) { return rsqrtf(ssq * (1.0f / 1024.0f) + EPS); }
; __device__ __forceinline__ u32x4 pack8(const f32x4 a, const f32x4 b) { u32x4 w; w.x = cvt_pk_bf16(a[0], a[1]); w.y = cvt_pk_bf16(a[2], a[3]); w.z = cvt_pk_bf16(b[0], b[1]); w.w = cvt_pk_bf16(b[2], b[3]); return w; }
;     __device__ __forceinline__ void operator()(const AccT& acc, const pg8::Unit& u, int wr, int wc, int fr, int fq) const {
;     ...
;                 const int r = EPI_ROW(u, ai, m); const float ri = rinv_of(ris[ai][m]);
;                 f32x4 o[2];
; #pragma unroll
;                 for (int n = 0; n < 2; ++n) { const f32x4 gt = acc[ai][0][m][n] * ri, up = acc[ai][1][m][n] * ri;
; #pragma unroll
;                     for (int j = 0; j < 4; ++j) o[n][j] = siluf_(gt[j]) * up[j]; }
;                 *(u32x4*)(act + (size_t)r * DFF + u.pn * 128 + wc * 32 + 8 * fq) = pack8(o[0], o[1]); }
	v_rcp_f32_e32 v167, v167
	v_pk_mul_f32 v[40:41], v[40:41], v[162:163] op_sel_hi:[1,0]
	v_pk_mul_f32 v[42:43], v[42:43], v[162:163] op_sel_hi:[1,0]
	v_pk_mul_f32 v[40:41], v[40:41], v[164:165]
	v_pk_mul_f32 v[42:43], v[42:43], v[166:167]
	v_pk_mul_f32 v[164:165], v[32:33], v[170:171] op_sel_hi:[1,0]
	v_pk_mul_f32 v[166:167], v[34:35], v[170:171] op_sel_hi:[1,0]
	v_exp_f32_e32 v164, v164
	v_exp_f32_e32 v165, v165
	v_exp_f32_e32 v166, v166
	v_exp_f32_e32 v167, v167
	v_pk_mul_f32 v[32:33], v[32:33], v[36:37]
	v_pk_mul_f32 v[34:35], v[34:35], v[38:39]
	v_add_f32_e32 v164, 1.0, v164
	v_add_f32_e32 v165, 1.0, v165
	v_add_f32_e32 v166, 1.0, v166
	v_add_f32_e32 v167, 1.0, v167
	v_rcp_f32_e32 v164, v164
	v_rcp_f32_e32 v165, v165
	v_rcp_f32_e32 v166, v166
	v_rcp_f32_e32 v167, v167
	v_pk_mul_f32 v[32:33], v[32:33], v[162:163] op_sel_hi:[1,0]
	v_pk_mul_f32 v[34:35], v[34:35], v[162:163] op_sel_hi:[1,0]
	v_pk_mul_f32 v[32:33], v[32:33], v[164:165]
	v_pk_mul_f32 v[34:35], v[34:35], v[166:167]
	v_cvt_pk_bf16_f32 v176, v40, v41
	v_cvt_pk_bf16_f32 v177, v42, v43
	v_cvt_pk_bf16_f32 v178, v32, v33
	v_cvt_pk_bf16_f32 v179, v34, v35
	global_store_dwordx4 v168, v[176:179], s[100:101]
	v_fmamk_f32 v162, v254, 0x3a800000, v188
	v_rsq_f32_e32 v162, v162
	v_add_u32_e32 v168, 0xdc000, v161
	s_nop 0
	v_mul_f32_e32 v170, 0xbfb8aa3b, v162
	v_mul_f32_e32 v162, v162, v162
	v_pk_mul_f32 v[164:165], v[24:25], v[170:171] op_sel_hi:[1,0]
	v_pk_mul_f32 v[166:167], v[26:27], v[170:171] op_sel_hi:[1,0]
	v_exp_f32_e32 v164, v164
	v_exp_f32_e32 v165, v165
	v_exp_f32_e32 v166, v166
	v_exp_f32_e32 v167, v167
	v_pk_mul_f32 v[24:25], v[24:25], v[28:29]
	v_pk_mul_f32 v[26:27], v[26:27], v[30:31]
	v_add_f32_e32 v164, 1.0, v164
	v_add_f32_e32 v165, 1.0, v165
	v_add_f32_e32 v166, 1.0, v166
	v_add_f32_e32 v167, 1.0, v167
	v_rcp_f32_e32 v164, v164
	v_rcp_f32_e32 v165, v165
	v_rcp_f32_e32 v166, v166
	v_rcp_f32_e32 v167, v167
	v_pk_mul_f32 v[24:25], v[24:25], v[162:163] op_sel_hi:[1,0]
	v_pk_mul_f32 v[26:27], v[26:27], v[162:163] op_sel_hi:[1,0]
	v_pk_mul_f32 v[24:25], v[24:25], v[164:165]
	v_pk_mul_f32 v[26:27], v[26:27], v[166:167]
	v_pk_mul_f32 v[164:165], v[16:17], v[170:171] op_sel_hi:[1,0]
	v_pk_mul_f32 v[166:167], v[18:19], v[170:171] op_sel_hi:[1,0]
	v_exp_f32_e32 v164, v164
	v_exp_f32_e32 v165, v165
	v_exp_f32_e32 v166, v166
	v_exp_f32_e32 v167, v167
	v_pk_mul_f32 v[16:17], v[16:17], v[20:21]
	v_pk_mul_f32 v[18:19], v[18:19], v[22:23]
	v_add_f32_e32 v164, 1.0, v164
	v_add_f32_e32 v165, 1.0, v165
	v_add_f32_e32 v166, 1.0, v166
	v_add_f32_e32 v167, 1.0, v167
	v_rcp_f32_e32 v164, v164
	v_rcp_f32_e32 v165, v165
	v_rcp_f32_e32 v166, v166
	v_rcp_f32_e32 v167, v167
	v_pk_mul_f32 v[16:17], v[16:17], v[162:163] op_sel_hi:[1,0]
	v_pk_mul_f32 v[18:19], v[18:19], v[162:163] op_sel_hi:[1,0]
	v_pk_mul_f32 v[16:17], v[16:17], v[164:165]
	v_pk_mul_f32 v[18:19], v[18:19], v[166:167]
	v_cvt_pk_bf16_f32 v172, v24, v25
	v_cvt_pk_bf16_f32 v173, v26, v27
	v_cvt_pk_bf16_f32 v174, v16, v17
	v_cvt_pk_bf16_f32 v175, v18, v19
	global_store_dwordx4 v168, v[172:175], s[100:101]
	v_fmamk_f32 v162, v255, 0x3a800000, v188
	v_rsq_f32_e32 v162, v162
	v_add_u32_e32 v168, 0xf2000, v161
	s_nop 0
	v_mul_f32_e32 v170, 0xbfb8aa3b, v162
	v_mul_f32_e32 v162, v162, v162
	v_pk_mul_f32 v[164:165], v[8:9], v[170:171] op_sel_hi:[1,0]
	v_pk_mul_f32 v[166:167], v[10:11], v[170:171] op_sel_hi:[1,0]
	v_exp_f32_e32 v164, v164
	v_exp_f32_e32 v165, v165
	v_exp_f32_e32 v166, v166
	v_exp_f32_e32 v167, v167
	v_pk_mul_f32 v[8:9], v[8:9], v[12:13]
	v_pk_mul_f32 v[10:11], v[10:11], v[14:15]
	v_add_f32_e32 v164, 1.0, v164
	v_add_f32_e32 v165, 1.0, v165
	v_add_f32_e32 v166, 1.0, v166
	v_add_f32_e32 v167, 1.0, v167
	v_rcp_f32_e32 v164, v164
	v_rcp_f32_e32 v165, v165
	v_rcp_f32_e32 v166, v166
	v_rcp_f32_e32 v167, v167
	v_pk_mul_f32 v[8:9], v[8:9], v[162:163] op_sel_hi:[1,0]
	v_pk_mul_f32 v[10:11], v[10:11], v[162:163] op_sel_hi:[1,0]
	v_pk_mul_f32 v[8:9], v[8:9], v[164:165]
	v_pk_mul_f32 v[10:11], v[10:11], v[166:167]
	v_pk_mul_f32 v[164:165], v[4:5], v[170:171] op_sel_hi:[1,0]
	v_pk_mul_f32 v[166:167], v[6:7], v[170:171] op_sel_hi:[1,0]
	v_exp_f32_e32 v164, v164
	v_exp_f32_e32 v165, v165
	v_exp_f32_e32 v166, v166
	v_exp_f32_e32 v167, v167
	v_pk_mul_f32 v[4:5], v[4:5], v[0:1]
	v_pk_mul_f32 v[6:7], v[6:7], v[2:3]
	v_add_f32_e32 v164, 1.0, v164
	v_add_f32_e32 v165, 1.0, v165
	v_add_f32_e32 v166, 1.0, v166
	v_add_f32_e32 v167, 1.0, v167
	v_rcp_f32_e32 v164, v164
	v_rcp_f32_e32 v165, v165
	v_rcp_f32_e32 v166, v166
	v_rcp_f32_e32 v167, v167
	v_pk_mul_f32 v[4:5], v[4:5], v[162:163] op_sel_hi:[1,0]
	v_pk_mul_f32 v[6:7], v[6:7], v[162:163] op_sel_hi:[1,0]
	v_pk_mul_f32 v[4:5], v[4:5], v[164:165]
	v_pk_mul_f32 v[6:7], v[6:7], v[166:167]
	v_cvt_pk_bf16_f32 v176, v8, v9
	v_cvt_pk_bf16_f32 v177, v10, v11
	v_cvt_pk_bf16_f32 v178, v4, v5
	v_cvt_pk_bf16_f32 v179, v6, v7
	global_store_dwordx4 v168, v[176:179], s[100:101]
	s_mov_b64 s[28:29], s[20:21]
	s_mov_b32 s25, s16
	s_mov_b32 s24, s18
	s_mov_b64 s[26:27], s[22:23]
	s_and_b64 vcc, exec, s[6:7]
	s_cbranch_vccnz .LBB0_2412
